# v14 + batched spatial-gating (gMLP) output epilogue: 16 bf16 u loads issued together per batch with immediate offsets, one wait, then bias add / multiply / convert / store (was a 128-step load-wait-st
# speedup vs baseline: 1.0044x; 1.0044x over previous
; __device__ __forceinline__ bf16_t f2bf(float f) { return (bf16_t)(pk2(f, 0.f) & 0xffffu); }
;   __device__ __forceinline__ void operator()(f32x16 (&acc)[2][2], int fbase, int tbase, int lane, const float (&pre)[2]) const {
;     const int r = lane & 31, h = lane >> 5;
;     const int g = tbase >> 13, chunk = (tbase & 8191) >> 6;
;     fbase -= g * 128;
;     if (fbase >= 128) return;
;     const float* bs = b_s + g * 128 + fbase + 4 * h;
; #pragma unroll
;     for (int qi = 0; qi < 2; ++qi) {
;       const unsigned tok0 = (unsigned)(chunk * 128 + fbase + 4 * h);
;       const unsigned uo = tok0 * 512u + (unsigned)(g * 64 + 32 * qi + r), mo = tok0 * 1024u + (unsigned)(g * 64 + 32 * qi + r);
; #pragma unroll
;       for (int pi = 0; pi < 2; ++pi)
; #pragma unroll
;         for (int i = 0; i < 16; ++i) {
;           const int io = 32 * pi + 8 * (i >> 2) + (i & 3);
;           const float uu = bf2f(ub[uo + (unsigned)(io * 512)]);
;           mix[mo + (unsigned)(io * 1024)] = f2bf(uu * (acc[pi][qi][i] + bs[io]));
;         }
;     }
.LBB0_564:
	s_waitcnt vmcnt(7)
	v_add_u32_e32 v129, s19, v171
	v_ashrrev_i32_e32 v130, 13, v129
	v_add_u32_e32 v128, s20, v174
	s_waitcnt vmcnt(4)
	v_lshlrev_b32_e32 v140, 7, v130
	v_sub_u32_e32 v142, v128, v140
	v_lshlrev_b32_e32 v128, 1, v129
	s_waitcnt vmcnt(3)
	v_lshl_or_b32 v147, v130, 6, v172
	v_cmp_gt_i32_e32 vcc, s3, v142
	v_ashrrev_i32_e32 v141, 31, v140
	v_lshlrev_b32_e32 v160, 2, v170
	s_waitcnt vmcnt(2)
	v_and_or_b32 v148, v128, s16, v170
	v_or_b32_e32 v146, 32, v147
	s_and_saveexec_b64 s[12:13], vcc
	s_cbranch_execz .LBB0_566
	v_lshl_add_u64 v[128:129], v[140:141], 2, s[6:7]
	v_ashrrev_i32_e32 v143, 31, v142
	v_lshl_add_u64 v[128:129], v[142:143], 2, v[128:129]
	v_add_lshl_u32 v149, v148, v142, 9
	v_lshl_add_u64 v[144:145], v[128:129], 0, v[160:161]
	v_lshl_add_u64 v[222:223], v[144:145], 0, 0
	s_mov_b32 s101, 0
	v_add_u32_e32 v128, v149, v147
	v_mov_b32_e32 v129, v161
	v_lshl_add_u64 v[214:215], v[128:129], 1, s[38:39]
	v_add_u32_e32 v128, v128, v149
	v_lshl_add_u64 v[218:219], v[128:129], 1, s[30:31]
	v_add_u32_e32 v128, v149, v146
	v_mov_b32_e32 v129, v161
	v_lshl_add_u64 v[216:217], v[128:129], 1, s[38:39]
	v_add_u32_e32 v128, v128, v149
	v_lshl_add_u64 v[220:221], v[128:129], 1, s[30:31]
	global_load_dwordx4 v[144:147], v[222:223], off offset:0
	global_load_dwordx4 v[148:151], v[222:223], off offset:32
	global_load_dwordx4 v[152:155], v[222:223], off offset:64
	global_load_dwordx4 v[156:159], v[222:223], off offset:96
	s_mov_b32 s100, 0x0
	v_lshl_add_u64 v[228:229], v[214:215], 0, s[100:101]
	global_load_ushort v176, v[228:229], off
	global_load_ushort v177, v[228:229], off offset:1024
	global_load_ushort v178, v[228:229], off offset:2048
	global_load_ushort v179, v[228:229], off offset:3072
	s_mov_b32 s100, 0x2000
	v_lshl_add_u64 v[230:231], v[214:215], 0, s[100:101]
	global_load_ushort v180, v[230:231], off
	global_load_ushort v181, v[230:231], off offset:1024
	global_load_ushort v182, v[230:231], off offset:2048
	global_load_ushort v183, v[230:231], off offset:3072
	s_mov_b32 s100, 0x4000
	v_lshl_add_u64 v[232:233], v[214:215], 0, s[100:101]
	global_load_ushort v184, v[232:233], off
	global_load_ushort v185, v[232:233], off offset:1024
	global_load_ushort v186, v[232:233], off offset:2048
	global_load_ushort v187, v[232:233], off offset:3072
	s_mov_b32 s100, 0x6000
	v_lshl_add_u64 v[234:235], v[214:215], 0, s[100:101]
	global_load_ushort v188, v[234:235], off
	global_load_ushort v189, v[234:235], off offset:1024
	global_load_ushort v190, v[234:235], off offset:2048
	global_load_ushort v191, v[234:235], off offset:3072
	s_mov_b32 s100, 0x0
	v_lshl_add_u64 v[236:237], v[218:219], 0, s[100:101]
	s_mov_b32 s100, 0x1000
	v_lshl_add_u64 v[238:239], v[218:219], 0, s[100:101]
	s_mov_b32 s100, 0x4000
	v_lshl_add_u64 v[240:241], v[218:219], 0, s[100:101]
	s_mov_b32 s100, 0x5000
	v_lshl_add_u64 v[242:243], v[218:219], 0, s[100:101]
	s_mov_b32 s100, 0x8000
	v_lshl_add_u64 v[244:245], v[218:219], 0, s[100:101]
	s_mov_b32 s100, 0x9000
	v_lshl_add_u64 v[246:247], v[218:219], 0, s[100:101]
	s_mov_b32 s100, 0xc000
	v_lshl_add_u64 v[248:249], v[218:219], 0, s[100:101]
	s_mov_b32 s100, 0xd000
	v_lshl_add_u64 v[250:251], v[218:219], 0, s[100:101]
	s_waitcnt vmcnt(0)
	v_lshlrev_b32_e32 v176, 16, v176
	v_add_f32_e32 v112, v112, v144
	v_lshlrev_b32_e32 v177, 16, v177
	v_add_f32_e32 v113, v113, v145
	v_lshlrev_b32_e32 v178, 16, v178
	v_add_f32_e32 v114, v114, v146
	v_lshlrev_b32_e32 v179, 16, v179
	v_add_f32_e32 v115, v115, v147
	v_lshlrev_b32_e32 v180, 16, v180
	v_add_f32_e32 v116, v116, v148
	v_lshlrev_b32_e32 v181, 16, v181
	v_add_f32_e32 v117, v117, v149
	v_lshlrev_b32_e32 v182, 16, v182
	v_add_f32_e32 v118, v118, v150
	v_lshlrev_b32_e32 v183, 16, v183
	v_add_f32_e32 v119, v119, v151
	v_lshlrev_b32_e32 v184, 16, v184
	v_add_f32_e32 v120, v120, v152
	v_lshlrev_b32_e32 v185, 16, v185
	v_add_f32_e32 v121, v121, v153
	v_lshlrev_b32_e32 v186, 16, v186
	v_add_f32_e32 v122, v122, v154
	v_lshlrev_b32_e32 v187, 16, v187
	v_add_f32_e32 v123, v123, v155
	v_lshlrev_b32_e32 v188, 16, v188
	v_add_f32_e32 v124, v124, v156
	v_lshlrev_b32_e32 v189, 16, v189
	v_add_f32_e32 v125, v125, v157
	v_lshlrev_b32_e32 v190, 16, v190
	v_add_f32_e32 v126, v126, v158
	v_lshlrev_b32_e32 v191, 16, v191
	v_add_f32_e32 v127, v127, v159
	v_mul_f32_e32 v112, v112, v176
	v_mul_f32_e32 v113, v113, v177
	v_mul_f32_e32 v114, v114, v178
	v_mul_f32_e32 v115, v115, v179
	v_mul_f32_e32 v116, v116, v180
	v_mul_f32_e32 v117, v117, v181
	v_mul_f32_e32 v118, v118, v182
	v_mul_f32_e32 v119, v119, v183
	v_mul_f32_e32 v120, v120, v184
	v_mul_f32_e32 v121, v121, v185
	v_mul_f32_e32 v122, v122, v186
	v_mul_f32_e32 v123, v123, v187
	v_mul_f32_e32 v124, v124, v188
	v_mul_f32_e32 v125, v125, v189
	v_mul_f32_e32 v126, v126, v190
	v_mul_f32_e32 v127, v127, v191
	v_cvt_pk_bf16_f32 v112, v112, v112
	v_cvt_pk_bf16_f32 v113, v113, v113
	v_cvt_pk_bf16_f32 v114, v114, v114
	v_cvt_pk_bf16_f32 v115, v115, v115
	v_cvt_pk_bf16_f32 v116, v116, v116
	v_cvt_pk_bf16_f32 v117, v117, v117
	v_cvt_pk_bf16_f32 v118, v118, v118
	v_cvt_pk_bf16_f32 v119, v119, v119
	v_cvt_pk_bf16_f32 v120, v120, v120
	v_cvt_pk_bf16_f32 v121, v121, v121
	v_cvt_pk_bf16_f32 v122, v122, v122
	v_cvt_pk_bf16_f32 v123, v123, v123
	v_cvt_pk_bf16_f32 v124, v124, v124
	v_cvt_pk_bf16_f32 v125, v125, v125
	v_cvt_pk_bf16_f32 v126, v126, v126
	v_cvt_pk_bf16_f32 v127, v127, v127
	global_store_short v[236:237], v112, off
	global_store_short v[236:237], v113, off offset:2048
	global_store_short v[238:239], v114, off
	global_store_short v[238:239], v115, off offset:2048
	global_store_short v[240:241], v116, off
	global_store_short v[240:241], v117, off offset:2048
; __device__ __forceinline__ bf16_t f2bf(float f) { return (bf16_t)(pk2(f, 0.f) & 0xffffu); }
;   __device__ __forceinline__ void operator()(f32x16 (&acc)[2][2], int fbase, int tbase, int lane, const float (&pre)[2]) const {
;     ...
;     for (int qi = 0; qi < 2; ++qi) {
;       const unsigned tok0 = (unsigned)(chunk * 128 + fbase + 4 * h);
;       const unsigned uo = tok0 * 512u + (unsigned)(g * 64 + 32 * qi + r), mo = tok0 * 1024u + (unsigned)(g * 64 + 32 * qi + r);
; #pragma unroll
;       for (int pi = 0; pi < 2; ++pi)
; #pragma unroll
;         for (int i = 0; i < 16; ++i) {
;           const int io = 32 * pi + 8 * (i >> 2) + (i & 3);
;           const float uu = bf2f(ub[uo + (unsigned)(io * 512)]);
;           mix[mo + (unsigned)(io * 1024)] = f2bf(uu * (acc[pi][qi][i] + bs[io]));
;         }
;     }
	global_store_short v[242:243], v118, off
	global_store_short v[242:243], v119, off offset:2048
	global_store_short v[244:245], v120, off
	global_store_short v[244:245], v121, off offset:2048
	global_store_short v[246:247], v122, off
	global_store_short v[246:247], v123, off offset:2048
	global_store_short v[248:249], v124, off
	global_store_short v[248:249], v125, off offset:2048
	global_store_short v[250:251], v126, off
	global_store_short v[250:251], v127, off offset:2048
	s_mov_b32 s100, 0x0
	v_lshl_add_u64 v[228:229], v[216:217], 0, s[100:101]
	global_load_ushort v176, v[228:229], off
	global_load_ushort v177, v[228:229], off offset:1024
	global_load_ushort v178, v[228:229], off offset:2048
	global_load_ushort v179, v[228:229], off offset:3072
	s_mov_b32 s100, 0x2000
	v_lshl_add_u64 v[230:231], v[216:217], 0, s[100:101]
	global_load_ushort v180, v[230:231], off
	global_load_ushort v181, v[230:231], off offset:1024
	global_load_ushort v182, v[230:231], off offset:2048
	global_load_ushort v183, v[230:231], off offset:3072
	s_mov_b32 s100, 0x4000
	v_lshl_add_u64 v[232:233], v[216:217], 0, s[100:101]
	global_load_ushort v184, v[232:233], off
	global_load_ushort v185, v[232:233], off offset:1024
	global_load_ushort v186, v[232:233], off offset:2048
	global_load_ushort v187, v[232:233], off offset:3072
	s_mov_b32 s100, 0x6000
	v_lshl_add_u64 v[234:235], v[216:217], 0, s[100:101]
	global_load_ushort v188, v[234:235], off
	global_load_ushort v189, v[234:235], off offset:1024
	global_load_ushort v190, v[234:235], off offset:2048
	global_load_ushort v191, v[234:235], off offset:3072
	s_mov_b32 s100, 0x0
	v_lshl_add_u64 v[236:237], v[220:221], 0, s[100:101]
	s_mov_b32 s100, 0x1000
	v_lshl_add_u64 v[238:239], v[220:221], 0, s[100:101]
	s_mov_b32 s100, 0x4000
	v_lshl_add_u64 v[240:241], v[220:221], 0, s[100:101]
	s_mov_b32 s100, 0x5000
	v_lshl_add_u64 v[242:243], v[220:221], 0, s[100:101]
	s_mov_b32 s100, 0x8000
	v_lshl_add_u64 v[244:245], v[220:221], 0, s[100:101]
	s_mov_b32 s100, 0x9000
	v_lshl_add_u64 v[246:247], v[220:221], 0, s[100:101]
	s_mov_b32 s100, 0xc000
	v_lshl_add_u64 v[248:249], v[220:221], 0, s[100:101]
	s_mov_b32 s100, 0xd000
	v_lshl_add_u64 v[250:251], v[220:221], 0, s[100:101]
	s_waitcnt vmcnt(0)
	v_lshlrev_b32_e32 v176, 16, v176
	v_add_f32_e32 v80, v80, v144
	v_lshlrev_b32_e32 v177, 16, v177
	v_add_f32_e32 v81, v81, v145
	v_lshlrev_b32_e32 v178, 16, v178
	v_add_f32_e32 v82, v82, v146
	v_lshlrev_b32_e32 v179, 16, v179
	v_add_f32_e32 v83, v83, v147
	v_lshlrev_b32_e32 v180, 16, v180
	v_add_f32_e32 v84, v84, v148
	v_lshlrev_b32_e32 v181, 16, v181
	v_add_f32_e32 v85, v85, v149
	v_lshlrev_b32_e32 v182, 16, v182
	v_add_f32_e32 v86, v86, v150
	v_lshlrev_b32_e32 v183, 16, v183
	v_add_f32_e32 v87, v87, v151
	v_lshlrev_b32_e32 v184, 16, v184
	v_add_f32_e32 v88, v88, v152
	v_lshlrev_b32_e32 v185, 16, v185
	v_add_f32_e32 v89, v89, v153
	v_lshlrev_b32_e32 v186, 16, v186
	v_add_f32_e32 v90, v90, v154
	v_lshlrev_b32_e32 v187, 16, v187
	v_add_f32_e32 v91, v91, v155
	v_lshlrev_b32_e32 v188, 16, v188
	v_add_f32_e32 v92, v92, v156
	v_lshlrev_b32_e32 v189, 16, v189
	v_add_f32_e32 v93, v93, v157
	v_lshlrev_b32_e32 v190, 16, v190
	v_add_f32_e32 v94, v94, v158
	v_lshlrev_b32_e32 v191, 16, v191
	v_add_f32_e32 v95, v95, v159
	v_mul_f32_e32 v80, v80, v176
	v_mul_f32_e32 v81, v81, v177
	v_mul_f32_e32 v82, v82, v178
	v_mul_f32_e32 v83, v83, v179
	v_mul_f32_e32 v84, v84, v180
	v_mul_f32_e32 v85, v85, v181
	v_mul_f32_e32 v86, v86, v182
	v_mul_f32_e32 v87, v87, v183
	v_mul_f32_e32 v88, v88, v184
	v_mul_f32_e32 v89, v89, v185
	v_mul_f32_e32 v90, v90, v186
	v_mul_f32_e32 v91, v91, v187
	v_mul_f32_e32 v92, v92, v188
	v_mul_f32_e32 v93, v93, v189
	v_mul_f32_e32 v94, v94, v190
	v_mul_f32_e32 v95, v95, v191
	v_cvt_pk_bf16_f32 v80, v80, v80
	v_cvt_pk_bf16_f32 v81, v81, v81
	v_cvt_pk_bf16_f32 v82, v82, v82
	v_cvt_pk_bf16_f32 v83, v83, v83
	v_cvt_pk_bf16_f32 v84, v84, v84
	v_cvt_pk_bf16_f32 v85, v85, v85
	v_cvt_pk_bf16_f32 v86, v86, v86
	v_cvt_pk_bf16_f32 v87, v87, v87
	v_cvt_pk_bf16_f32 v88, v88, v88
	v_cvt_pk_bf16_f32 v89, v89, v89
	v_cvt_pk_bf16_f32 v90, v90, v90
	v_cvt_pk_bf16_f32 v91, v91, v91
	v_cvt_pk_bf16_f32 v92, v92, v92
	v_cvt_pk_bf16_f32 v93, v93, v93
	v_cvt_pk_bf16_f32 v94, v94, v94
	v_cvt_pk_bf16_f32 v95, v95, v95
	global_store_short v[236:237], v80, off
	global_store_short v[236:237], v81, off offset:2048
	global_store_short v[238:239], v82, off
	global_store_short v[238:239], v83, off offset:2048
	global_store_short v[240:241], v84, off
	global_store_short v[240:241], v85, off offset:2048
	global_store_short v[242:243], v86, off
	global_store_short v[242:243], v87, off offset:2048
	global_store_short v[244:245], v88, off
	global_store_short v[244:245], v89, off offset:2048
	global_store_short v[246:247], v90, off
	global_store_short v[246:247], v91, off offset:2048
	global_store_short v[248:249], v92, off
	global_store_short v[248:249], v93, off offset:2048
	global_store_short v[250:251], v94, off
	global_store_short v[250:251], v95, off offset:2048
	global_load_dwordx4 v[144:147], v[222:223], off offset:128
	global_load_dwordx4 v[148:151], v[222:223], off offset:160
	global_load_dwordx4 v[152:155], v[222:223], off offset:192
	global_load_dwordx4 v[156:159], v[222:223], off offset:224
	s_mov_b32 s100, 0x8000
	v_lshl_add_u64 v[228:229], v[214:215], 0, s[100:101]
	global_load_ushort v176, v[228:229], off
	global_load_ushort v177, v[228:229], off offset:1024
	global_load_ushort v178, v[228:229], off offset:2048
	global_load_ushort v179, v[228:229], off offset:3072
	s_mov_b32 s100, 0xa000
	v_lshl_add_u64 v[230:231], v[214:215], 0, s[100:101]
	global_load_ushort v180, v[230:231], off
	global_load_ushort v181, v[230:231], off offset:1024
	global_load_ushort v182, v[230:231], off offset:2048
	global_load_ushort v183, v[230:231], off offset:3072
	s_mov_b32 s100, 0xc000
	v_lshl_add_u64 v[232:233], v[214:215], 0, s[100:101]
	global_load_ushort v184, v[232:233], off
	global_load_ushort v185, v[232:233], off offset:1024
	global_load_ushort v186, v[232:233], off offset:2048
	global_load_ushort v187, v[232:233], off offset:3072
	s_mov_b32 s100, 0xe000
	v_lshl_add_u64 v[234:235], v[214:215], 0, s[100:101]
	global_load_ushort v188, v[234:235], off
	global_load_ushort v189, v[234:235], off offset:1024
	global_load_ushort v190, v[234:235], off offset:2048
	global_load_ushort v191, v[234:235], off offset:3072
	s_mov_b32 s100, 0x10000
	v_lshl_add_u64 v[236:237], v[218:219], 0, s[100:101]
	s_mov_b32 s100, 0x11000
	v_lshl_add_u64 v[238:239], v[218:219], 0, s[100:101]
	s_mov_b32 s100, 0x14000
	v_lshl_add_u64 v[240:241], v[218:219], 0, s[100:101]
	s_mov_b32 s100, 0x15000
	v_lshl_add_u64 v[242:243], v[218:219], 0, s[100:101]
	s_mov_b32 s100, 0x18000
	v_lshl_add_u64 v[244:245], v[218:219], 0, s[100:101]
	s_mov_b32 s100, 0x19000
	v_lshl_add_u64 v[246:247], v[218:219], 0, s[100:101]
	s_mov_b32 s100, 0x1c000
	v_lshl_add_u64 v[248:249], v[218:219], 0, s[100:101]
	s_mov_b32 s100, 0x1d000
	v_lshl_add_u64 v[250:251], v[218:219], 0, s[100:101]
	s_waitcnt vmcnt(0)
; __device__ __forceinline__ bf16_t f2bf(float f) { return (bf16_t)(pk2(f, 0.f) & 0xffffu); }
;   __device__ __forceinline__ void operator()(f32x16 (&acc)[2][2], int fbase, int tbase, int lane, const float (&pre)[2]) const {
;     ...
;     for (int qi = 0; qi < 2; ++qi) {
;       const unsigned tok0 = (unsigned)(chunk * 128 + fbase + 4 * h);
;       const unsigned uo = tok0 * 512u + (unsigned)(g * 64 + 32 * qi + r), mo = tok0 * 1024u + (unsigned)(g * 64 + 32 * qi + r);
; #pragma unroll
;       for (int pi = 0; pi < 2; ++pi)
; #pragma unroll
;         for (int i = 0; i < 16; ++i) {
;           const int io = 32 * pi + 8 * (i >> 2) + (i & 3);
;           const float uu = bf2f(ub[uo + (unsigned)(io * 512)]);
;           mix[mo + (unsigned)(io * 1024)] = f2bf(uu * (acc[pi][qi][i] + bs[io]));
;         }
;     }
	v_lshlrev_b32_e32 v176, 16, v176
	v_add_f32_e32 v96, v96, v144
	v_lshlrev_b32_e32 v177, 16, v177
	v_add_f32_e32 v97, v97, v145
	v_lshlrev_b32_e32 v178, 16, v178
	v_add_f32_e32 v98, v98, v146
	v_lshlrev_b32_e32 v179, 16, v179
	v_add_f32_e32 v99, v99, v147
	v_lshlrev_b32_e32 v180, 16, v180
	v_add_f32_e32 v100, v100, v148
	v_lshlrev_b32_e32 v181, 16, v181
	v_add_f32_e32 v101, v101, v149
	v_lshlrev_b32_e32 v182, 16, v182
	v_add_f32_e32 v102, v102, v150
	v_lshlrev_b32_e32 v183, 16, v183
	v_add_f32_e32 v103, v103, v151
	v_lshlrev_b32_e32 v184, 16, v184
	v_add_f32_e32 v104, v104, v152
	v_lshlrev_b32_e32 v185, 16, v185
	v_add_f32_e32 v105, v105, v153
	v_lshlrev_b32_e32 v186, 16, v186
	v_add_f32_e32 v106, v106, v154
	v_lshlrev_b32_e32 v187, 16, v187
	v_add_f32_e32 v107, v107, v155
	v_lshlrev_b32_e32 v188, 16, v188
	v_add_f32_e32 v108, v108, v156
	v_lshlrev_b32_e32 v189, 16, v189
	v_add_f32_e32 v109, v109, v157
	v_lshlrev_b32_e32 v190, 16, v190
	v_add_f32_e32 v110, v110, v158
	v_lshlrev_b32_e32 v191, 16, v191
	v_add_f32_e32 v111, v111, v159
	v_mul_f32_e32 v96, v96, v176
	v_mul_f32_e32 v97, v97, v177
	v_mul_f32_e32 v98, v98, v178
	v_mul_f32_e32 v99, v99, v179
	v_mul_f32_e32 v100, v100, v180
	v_mul_f32_e32 v101, v101, v181
	v_mul_f32_e32 v102, v102, v182
	v_mul_f32_e32 v103, v103, v183
	v_mul_f32_e32 v104, v104, v184
	v_mul_f32_e32 v105, v105, v185
	v_mul_f32_e32 v106, v106, v186
	v_mul_f32_e32 v107, v107, v187
	v_mul_f32_e32 v108, v108, v188
	v_mul_f32_e32 v109, v109, v189
	v_mul_f32_e32 v110, v110, v190
	v_mul_f32_e32 v111, v111, v191
	v_cvt_pk_bf16_f32 v96, v96, v96
	v_cvt_pk_bf16_f32 v97, v97, v97
	v_cvt_pk_bf16_f32 v98, v98, v98
	v_cvt_pk_bf16_f32 v99, v99, v99
	v_cvt_pk_bf16_f32 v100, v100, v100
	v_cvt_pk_bf16_f32 v101, v101, v101
	v_cvt_pk_bf16_f32 v102, v102, v102
	v_cvt_pk_bf16_f32 v103, v103, v103
	v_cvt_pk_bf16_f32 v104, v104, v104
	v_cvt_pk_bf16_f32 v105, v105, v105
	v_cvt_pk_bf16_f32 v106, v106, v106
	v_cvt_pk_bf16_f32 v107, v107, v107
	v_cvt_pk_bf16_f32 v108, v108, v108
	v_cvt_pk_bf16_f32 v109, v109, v109
	v_cvt_pk_bf16_f32 v110, v110, v110
	v_cvt_pk_bf16_f32 v111, v111, v111
	global_store_short v[236:237], v96, off
	global_store_short v[236:237], v97, off offset:2048
	global_store_short v[238:239], v98, off
	global_store_short v[238:239], v99, off offset:2048
	global_store_short v[240:241], v100, off
	global_store_short v[240:241], v101, off offset:2048
	global_store_short v[242:243], v102, off
	global_store_short v[242:243], v103, off offset:2048
	global_store_short v[244:245], v104, off
	global_store_short v[244:245], v105, off offset:2048
	global_store_short v[246:247], v106, off
	global_store_short v[246:247], v107, off offset:2048
	global_store_short v[248:249], v108, off
	global_store_short v[248:249], v109, off offset:2048
	global_store_short v[250:251], v110, off
	global_store_short v[250:251], v111, off offset:2048
	s_mov_b32 s100, 0x8000
	v_lshl_add_u64 v[228:229], v[216:217], 0, s[100:101]
	global_load_ushort v176, v[228:229], off
	global_load_ushort v177, v[228:229], off offset:1024
	global_load_ushort v178, v[228:229], off offset:2048
	global_load_ushort v179, v[228:229], off offset:3072
	s_mov_b32 s100, 0xa000
	v_lshl_add_u64 v[230:231], v[216:217], 0, s[100:101]
	global_load_ushort v180, v[230:231], off
	global_load_ushort v181, v[230:231], off offset:1024
	global_load_ushort v182, v[230:231], off offset:2048
	global_load_ushort v183, v[230:231], off offset:3072
	s_mov_b32 s100, 0xc000
	v_lshl_add_u64 v[232:233], v[216:217], 0, s[100:101]
	global_load_ushort v184, v[232:233], off
	global_load_ushort v185, v[232:233], off offset:1024
	global_load_ushort v186, v[232:233], off offset:2048
	global_load_ushort v187, v[232:233], off offset:3072
	s_mov_b32 s100, 0xe000
	v_lshl_add_u64 v[234:235], v[216:217], 0, s[100:101]
	global_load_ushort v188, v[234:235], off
	global_load_ushort v189, v[234:235], off offset:1024
	global_load_ushort v190, v[234:235], off offset:2048
	global_load_ushort v191, v[234:235], off offset:3072
	s_mov_b32 s100, 0x10000
	v_lshl_add_u64 v[236:237], v[220:221], 0, s[100:101]
	s_mov_b32 s100, 0x11000
	v_lshl_add_u64 v[238:239], v[220:221], 0, s[100:101]
	s_mov_b32 s100, 0x14000
	v_lshl_add_u64 v[240:241], v[220:221], 0, s[100:101]
	s_mov_b32 s100, 0x15000
	v_lshl_add_u64 v[242:243], v[220:221], 0, s[100:101]
	s_mov_b32 s100, 0x18000
	v_lshl_add_u64 v[244:245], v[220:221], 0, s[100:101]
	s_mov_b32 s100, 0x19000
	v_lshl_add_u64 v[246:247], v[220:221], 0, s[100:101]
	s_mov_b32 s100, 0x1c000
	v_lshl_add_u64 v[248:249], v[220:221], 0, s[100:101]
	s_mov_b32 s100, 0x1d000
	v_lshl_add_u64 v[250:251], v[220:221], 0, s[100:101]
	s_waitcnt vmcnt(0)
; __device__ __forceinline__ bf16_t f2bf(float f) { return (bf16_t)(pk2(f, 0.f) & 0xffffu); }
;   __device__ __forceinline__ void operator()(f32x16 (&acc)[2][2], int fbase, int tbase, int lane, const float (&pre)[2]) const {
;     ...
;     for (int qi = 0; qi < 2; ++qi) {
;       const unsigned tok0 = (unsigned)(chunk * 128 + fbase + 4 * h);
;       const unsigned uo = tok0 * 512u + (unsigned)(g * 64 + 32 * qi + r), mo = tok0 * 1024u + (unsigned)(g * 64 + 32 * qi + r);
; #pragma unroll
;       for (int pi = 0; pi < 2; ++pi)
; #pragma unroll
;         for (int i = 0; i < 16; ++i) {
;           const int io = 32 * pi + 8 * (i >> 2) + (i & 3);
;           const float uu = bf2f(ub[uo + (unsigned)(io * 512)]);
;           mix[mo + (unsigned)(io * 1024)] = f2bf(uu * (acc[pi][qi][i] + bs[io]));
;         }
;     }
	v_lshlrev_b32_e32 v176, 16, v176
	v_add_f32_e32 v64, v64, v144
	v_lshlrev_b32_e32 v177, 16, v177
	v_add_f32_e32 v65, v65, v145
	v_lshlrev_b32_e32 v178, 16, v178
	v_add_f32_e32 v66, v66, v146
	v_lshlrev_b32_e32 v179, 16, v179
	v_add_f32_e32 v67, v67, v147
	v_lshlrev_b32_e32 v180, 16, v180
	v_add_f32_e32 v68, v68, v148
	v_lshlrev_b32_e32 v181, 16, v181
	v_add_f32_e32 v69, v69, v149
	v_lshlrev_b32_e32 v182, 16, v182
	v_add_f32_e32 v70, v70, v150
	v_lshlrev_b32_e32 v183, 16, v183
	v_add_f32_e32 v71, v71, v151
	v_lshlrev_b32_e32 v184, 16, v184
	v_add_f32_e32 v72, v72, v152
	v_lshlrev_b32_e32 v185, 16, v185
	v_add_f32_e32 v73, v73, v153
	v_lshlrev_b32_e32 v186, 16, v186
	v_add_f32_e32 v74, v74, v154
	v_lshlrev_b32_e32 v187, 16, v187
	v_add_f32_e32 v75, v75, v155
	v_lshlrev_b32_e32 v188, 16, v188
	v_add_f32_e32 v76, v76, v156
	v_lshlrev_b32_e32 v189, 16, v189
	v_add_f32_e32 v77, v77, v157
	v_lshlrev_b32_e32 v190, 16, v190
	v_add_f32_e32 v78, v78, v158
	v_lshlrev_b32_e32 v191, 16, v191
	v_add_f32_e32 v79, v79, v159
	v_mul_f32_e32 v64, v64, v176
	v_mul_f32_e32 v65, v65, v177
	v_mul_f32_e32 v66, v66, v178
	v_mul_f32_e32 v67, v67, v179
	v_mul_f32_e32 v68, v68, v180
	v_mul_f32_e32 v69, v69, v181
	v_mul_f32_e32 v70, v70, v182
	v_mul_f32_e32 v71, v71, v183
	v_mul_f32_e32 v72, v72, v184
	v_mul_f32_e32 v73, v73, v185
	v_mul_f32_e32 v74, v74, v186
	v_mul_f32_e32 v75, v75, v187
	v_mul_f32_e32 v76, v76, v188
	v_mul_f32_e32 v77, v77, v189
	v_mul_f32_e32 v78, v78, v190
	v_mul_f32_e32 v79, v79, v191
	v_cvt_pk_bf16_f32 v64, v64, v64
	v_cvt_pk_bf16_f32 v65, v65, v65
	v_cvt_pk_bf16_f32 v66, v66, v66
	v_cvt_pk_bf16_f32 v67, v67, v67
	v_cvt_pk_bf16_f32 v68, v68, v68
	v_cvt_pk_bf16_f32 v69, v69, v69
	v_cvt_pk_bf16_f32 v70, v70, v70
	v_cvt_pk_bf16_f32 v71, v71, v71
	v_cvt_pk_bf16_f32 v72, v72, v72
	v_cvt_pk_bf16_f32 v73, v73, v73
	v_cvt_pk_bf16_f32 v74, v74, v74
	v_cvt_pk_bf16_f32 v75, v75, v75
	v_cvt_pk_bf16_f32 v76, v76, v76
	v_cvt_pk_bf16_f32 v77, v77, v77
	v_cvt_pk_bf16_f32 v78, v78, v78
	v_cvt_pk_bf16_f32 v79, v79, v79
	global_store_short v[236:237], v64, off
	global_store_short v[236:237], v65, off offset:2048
	global_store_short v[238:239], v66, off
	global_store_short v[238:239], v67, off offset:2048
	global_store_short v[240:241], v68, off
	global_store_short v[240:241], v69, off offset:2048
	global_store_short v[242:243], v70, off
	global_store_short v[242:243], v71, off offset:2048
	global_store_short v[244:245], v72, off
	global_store_short v[244:245], v73, off offset:2048
	global_store_short v[246:247], v74, off
	global_store_short v[246:247], v75, off offset:2048
	global_store_short v[248:249], v76, off
	global_store_short v[248:249], v77, off offset:2048
	global_store_short v[250:251], v78, off
	global_store_short v[250:251], v79, off offset:2048
	global_load_dwordx4 v[144:147], v[222:223], off offset:256
	global_load_dwordx4 v[148:151], v[222:223], off offset:288
	global_load_dwordx4 v[152:155], v[222:223], off offset:320
	global_load_dwordx4 v[156:159], v[222:223], off offset:352
	s_mov_b32 s100, 0x10000
	v_lshl_add_u64 v[228:229], v[214:215], 0, s[100:101]
	global_load_ushort v176, v[228:229], off
	global_load_ushort v177, v[228:229], off offset:1024
	global_load_ushort v178, v[228:229], off offset:2048
	global_load_ushort v179, v[228:229], off offset:3072
	s_mov_b32 s100, 0x12000
	v_lshl_add_u64 v[230:231], v[214:215], 0, s[100:101]
	global_load_ushort v180, v[230:231], off
	global_load_ushort v181, v[230:231], off offset:1024
	global_load_ushort v182, v[230:231], off offset:2048
	global_load_ushort v183, v[230:231], off offset:3072
	s_mov_b32 s100, 0x14000
	v_lshl_add_u64 v[232:233], v[214:215], 0, s[100:101]
	global_load_ushort v184, v[232:233], off
	global_load_ushort v185, v[232:233], off offset:1024
	global_load_ushort v186, v[232:233], off offset:2048
	global_load_ushort v187, v[232:233], off offset:3072
	s_mov_b32 s100, 0x16000
	v_lshl_add_u64 v[234:235], v[214:215], 0, s[100:101]
	global_load_ushort v188, v[234:235], off
	global_load_ushort v189, v[234:235], off offset:1024
	global_load_ushort v190, v[234:235], off offset:2048
	global_load_ushort v191, v[234:235], off offset:3072
	s_mov_b32 s100, 0x20000
	v_lshl_add_u64 v[236:237], v[218:219], 0, s[100:101]
	s_mov_b32 s100, 0x21000
	v_lshl_add_u64 v[238:239], v[218:219], 0, s[100:101]
	s_mov_b32 s100, 0x24000
	v_lshl_add_u64 v[240:241], v[218:219], 0, s[100:101]
	s_mov_b32 s100, 0x25000
	v_lshl_add_u64 v[242:243], v[218:219], 0, s[100:101]
	s_mov_b32 s100, 0x28000
	v_lshl_add_u64 v[244:245], v[218:219], 0, s[100:101]
	s_mov_b32 s100, 0x29000
	v_lshl_add_u64 v[246:247], v[218:219], 0, s[100:101]
	s_mov_b32 s100, 0x2c000
	v_lshl_add_u64 v[248:249], v[218:219], 0, s[100:101]
	s_mov_b32 s100, 0x2d000
	v_lshl_add_u64 v[250:251], v[218:219], 0, s[100:101]
	s_waitcnt vmcnt(0)
; __device__ __forceinline__ bf16_t f2bf(float f) { return (bf16_t)(pk2(f, 0.f) & 0xffffu); }
;   __device__ __forceinline__ void operator()(f32x16 (&acc)[2][2], int fbase, int tbase, int lane, const float (&pre)[2]) const {
;     ...
;     for (int qi = 0; qi < 2; ++qi) {
;       const unsigned tok0 = (unsigned)(chunk * 128 + fbase + 4 * h);
;       const unsigned uo = tok0 * 512u + (unsigned)(g * 64 + 32 * qi + r), mo = tok0 * 1024u + (unsigned)(g * 64 + 32 * qi + r);
; #pragma unroll
;       for (int pi = 0; pi < 2; ++pi)
; #pragma unroll
;         for (int i = 0; i < 16; ++i) {
;           const int io = 32 * pi + 8 * (i >> 2) + (i & 3);
;           const float uu = bf2f(ub[uo + (unsigned)(io * 512)]);
;           mix[mo + (unsigned)(io * 1024)] = f2bf(uu * (acc[pi][qi][i] + bs[io]));
;         }
;     }
	v_lshlrev_b32_e32 v176, 16, v176
	v_add_f32_e32 v48, v48, v144
	v_lshlrev_b32_e32 v177, 16, v177
	v_add_f32_e32 v49, v49, v145
	v_lshlrev_b32_e32 v178, 16, v178
	v_add_f32_e32 v50, v50, v146
	v_lshlrev_b32_e32 v179, 16, v179
	v_add_f32_e32 v51, v51, v147
	v_lshlrev_b32_e32 v180, 16, v180
	v_add_f32_e32 v52, v52, v148
	v_lshlrev_b32_e32 v181, 16, v181
	v_add_f32_e32 v53, v53, v149
	v_lshlrev_b32_e32 v182, 16, v182
	v_add_f32_e32 v54, v54, v150
	v_lshlrev_b32_e32 v183, 16, v183
	v_add_f32_e32 v55, v55, v151
	v_lshlrev_b32_e32 v184, 16, v184
	v_add_f32_e32 v56, v56, v152
	v_lshlrev_b32_e32 v185, 16, v185
	v_add_f32_e32 v57, v57, v153
	v_lshlrev_b32_e32 v186, 16, v186
	v_add_f32_e32 v58, v58, v154
	v_lshlrev_b32_e32 v187, 16, v187
	v_add_f32_e32 v59, v59, v155
	v_lshlrev_b32_e32 v188, 16, v188
	v_add_f32_e32 v60, v60, v156
	v_lshlrev_b32_e32 v189, 16, v189
	v_add_f32_e32 v61, v61, v157
	v_lshlrev_b32_e32 v190, 16, v190
	v_add_f32_e32 v62, v62, v158
	v_lshlrev_b32_e32 v191, 16, v191
	v_add_f32_e32 v63, v63, v159
	v_mul_f32_e32 v48, v48, v176
	v_mul_f32_e32 v49, v49, v177
	v_mul_f32_e32 v50, v50, v178
	v_mul_f32_e32 v51, v51, v179
	v_mul_f32_e32 v52, v52, v180
	v_mul_f32_e32 v53, v53, v181
	v_mul_f32_e32 v54, v54, v182
	v_mul_f32_e32 v55, v55, v183
	v_mul_f32_e32 v56, v56, v184
	v_mul_f32_e32 v57, v57, v185
	v_mul_f32_e32 v58, v58, v186
	v_mul_f32_e32 v59, v59, v187
	v_mul_f32_e32 v60, v60, v188
	v_mul_f32_e32 v61, v61, v189
	v_mul_f32_e32 v62, v62, v190
	v_mul_f32_e32 v63, v63, v191
	v_cvt_pk_bf16_f32 v48, v48, v48
	v_cvt_pk_bf16_f32 v49, v49, v49
	v_cvt_pk_bf16_f32 v50, v50, v50
	v_cvt_pk_bf16_f32 v51, v51, v51
	v_cvt_pk_bf16_f32 v52, v52, v52
	v_cvt_pk_bf16_f32 v53, v53, v53
	v_cvt_pk_bf16_f32 v54, v54, v54
	v_cvt_pk_bf16_f32 v55, v55, v55
	v_cvt_pk_bf16_f32 v56, v56, v56
	v_cvt_pk_bf16_f32 v57, v57, v57
	v_cvt_pk_bf16_f32 v58, v58, v58
	v_cvt_pk_bf16_f32 v59, v59, v59
	v_cvt_pk_bf16_f32 v60, v60, v60
	v_cvt_pk_bf16_f32 v61, v61, v61
	v_cvt_pk_bf16_f32 v62, v62, v62
	v_cvt_pk_bf16_f32 v63, v63, v63
	global_store_short v[236:237], v48, off
	global_store_short v[236:237], v49, off offset:2048
	global_store_short v[238:239], v50, off
	global_store_short v[238:239], v51, off offset:2048
	global_store_short v[240:241], v52, off
	global_store_short v[240:241], v53, off offset:2048
	global_store_short v[242:243], v54, off
	global_store_short v[242:243], v55, off offset:2048
	global_store_short v[244:245], v56, off
	global_store_short v[244:245], v57, off offset:2048
	global_store_short v[246:247], v58, off
	global_store_short v[246:247], v59, off offset:2048
	global_store_short v[248:249], v60, off
	global_store_short v[248:249], v61, off offset:2048
	global_store_short v[250:251], v62, off
	global_store_short v[250:251], v63, off offset:2048
	s_mov_b32 s100, 0x10000
	v_lshl_add_u64 v[228:229], v[216:217], 0, s[100:101]
	global_load_ushort v176, v[228:229], off
	global_load_ushort v177, v[228:229], off offset:1024
	global_load_ushort v178, v[228:229], off offset:2048
	global_load_ushort v179, v[228:229], off offset:3072
	s_mov_b32 s100, 0x12000
	v_lshl_add_u64 v[230:231], v[216:217], 0, s[100:101]
	global_load_ushort v180, v[230:231], off
	global_load_ushort v181, v[230:231], off offset:1024
	global_load_ushort v182, v[230:231], off offset:2048
	global_load_ushort v183, v[230:231], off offset:3072
	s_mov_b32 s100, 0x14000
	v_lshl_add_u64 v[232:233], v[216:217], 0, s[100:101]
	global_load_ushort v184, v[232:233], off
	global_load_ushort v185, v[232:233], off offset:1024
	global_load_ushort v186, v[232:233], off offset:2048
	global_load_ushort v187, v[232:233], off offset:3072
	s_mov_b32 s100, 0x16000
	v_lshl_add_u64 v[234:235], v[216:217], 0, s[100:101]
	global_load_ushort v188, v[234:235], off
	global_load_ushort v189, v[234:235], off offset:1024
	global_load_ushort v190, v[234:235], off offset:2048
	global_load_ushort v191, v[234:235], off offset:3072
	s_mov_b32 s100, 0x20000
	v_lshl_add_u64 v[236:237], v[220:221], 0, s[100:101]
	s_mov_b32 s100, 0x21000
	v_lshl_add_u64 v[238:239], v[220:221], 0, s[100:101]
	s_mov_b32 s100, 0x24000
	v_lshl_add_u64 v[240:241], v[220:221], 0, s[100:101]
	s_mov_b32 s100, 0x25000
	v_lshl_add_u64 v[242:243], v[220:221], 0, s[100:101]
	s_mov_b32 s100, 0x28000
	v_lshl_add_u64 v[244:245], v[220:221], 0, s[100:101]
	s_mov_b32 s100, 0x29000
	v_lshl_add_u64 v[246:247], v[220:221], 0, s[100:101]
	s_mov_b32 s100, 0x2c000
	v_lshl_add_u64 v[248:249], v[220:221], 0, s[100:101]
	s_mov_b32 s100, 0x2d000
	v_lshl_add_u64 v[250:251], v[220:221], 0, s[100:101]
	s_waitcnt vmcnt(0)
; __device__ __forceinline__ bf16_t f2bf(float f) { return (bf16_t)(pk2(f, 0.f) & 0xffffu); }
;   __device__ __forceinline__ void operator()(f32x16 (&acc)[2][2], int fbase, int tbase, int lane, const float (&pre)[2]) const {
;     ...
;     for (int qi = 0; qi < 2; ++qi) {
;       const unsigned tok0 = (unsigned)(chunk * 128 + fbase + 4 * h);
;       const unsigned uo = tok0 * 512u + (unsigned)(g * 64 + 32 * qi + r), mo = tok0 * 1024u + (unsigned)(g * 64 + 32 * qi + r);
; #pragma unroll
;       for (int pi = 0; pi < 2; ++pi)
; #pragma unroll
;         for (int i = 0; i < 16; ++i) {
;           const int io = 32 * pi + 8 * (i >> 2) + (i & 3);
;           const float uu = bf2f(ub[uo + (unsigned)(io * 512)]);
;           mix[mo + (unsigned)(io * 1024)] = f2bf(uu * (acc[pi][qi][i] + bs[io]));
;         }
;     }
	v_lshlrev_b32_e32 v176, 16, v176
	v_add_f32_e32 v16, v16, v144
	v_lshlrev_b32_e32 v177, 16, v177
	v_add_f32_e32 v17, v17, v145
	v_lshlrev_b32_e32 v178, 16, v178
	v_add_f32_e32 v18, v18, v146
	v_lshlrev_b32_e32 v179, 16, v179
	v_add_f32_e32 v19, v19, v147
	v_lshlrev_b32_e32 v180, 16, v180
	v_add_f32_e32 v20, v20, v148
	v_lshlrev_b32_e32 v181, 16, v181
	v_add_f32_e32 v21, v21, v149
	v_lshlrev_b32_e32 v182, 16, v182
	v_add_f32_e32 v22, v22, v150
	v_lshlrev_b32_e32 v183, 16, v183
	v_add_f32_e32 v23, v23, v151
	v_lshlrev_b32_e32 v184, 16, v184
	v_add_f32_e32 v24, v24, v152
	v_lshlrev_b32_e32 v185, 16, v185
	v_add_f32_e32 v25, v25, v153
	v_lshlrev_b32_e32 v186, 16, v186
	v_add_f32_e32 v26, v26, v154
	v_lshlrev_b32_e32 v187, 16, v187
	v_add_f32_e32 v27, v27, v155
	v_lshlrev_b32_e32 v188, 16, v188
	v_add_f32_e32 v28, v28, v156
	v_lshlrev_b32_e32 v189, 16, v189
	v_add_f32_e32 v29, v29, v157
	v_lshlrev_b32_e32 v190, 16, v190
	v_add_f32_e32 v30, v30, v158
	v_lshlrev_b32_e32 v191, 16, v191
	v_add_f32_e32 v31, v31, v159
	v_mul_f32_e32 v16, v16, v176
	v_mul_f32_e32 v17, v17, v177
	v_mul_f32_e32 v18, v18, v178
	v_mul_f32_e32 v19, v19, v179
	v_mul_f32_e32 v20, v20, v180
	v_mul_f32_e32 v21, v21, v181
	v_mul_f32_e32 v22, v22, v182
	v_mul_f32_e32 v23, v23, v183
	v_mul_f32_e32 v24, v24, v184
	v_mul_f32_e32 v25, v25, v185
	v_mul_f32_e32 v26, v26, v186
	v_mul_f32_e32 v27, v27, v187
	v_mul_f32_e32 v28, v28, v188
	v_mul_f32_e32 v29, v29, v189
	v_mul_f32_e32 v30, v30, v190
	v_mul_f32_e32 v31, v31, v191
	v_cvt_pk_bf16_f32 v16, v16, v16
	v_cvt_pk_bf16_f32 v17, v17, v17
	v_cvt_pk_bf16_f32 v18, v18, v18
	v_cvt_pk_bf16_f32 v19, v19, v19
	v_cvt_pk_bf16_f32 v20, v20, v20
	v_cvt_pk_bf16_f32 v21, v21, v21
	v_cvt_pk_bf16_f32 v22, v22, v22
	v_cvt_pk_bf16_f32 v23, v23, v23
	v_cvt_pk_bf16_f32 v24, v24, v24
	v_cvt_pk_bf16_f32 v25, v25, v25
	v_cvt_pk_bf16_f32 v26, v26, v26
	v_cvt_pk_bf16_f32 v27, v27, v27
	v_cvt_pk_bf16_f32 v28, v28, v28
	v_cvt_pk_bf16_f32 v29, v29, v29
	v_cvt_pk_bf16_f32 v30, v30, v30
	v_cvt_pk_bf16_f32 v31, v31, v31
	global_store_short v[236:237], v16, off
	global_store_short v[236:237], v17, off offset:2048
	global_store_short v[238:239], v18, off
	global_store_short v[238:239], v19, off offset:2048
	global_store_short v[240:241], v20, off
	global_store_short v[240:241], v21, off offset:2048
	global_store_short v[242:243], v22, off
	global_store_short v[242:243], v23, off offset:2048
	global_store_short v[244:245], v24, off
	global_store_short v[244:245], v25, off offset:2048
	global_store_short v[246:247], v26, off
	global_store_short v[246:247], v27, off offset:2048
	global_store_short v[248:249], v28, off
	global_store_short v[248:249], v29, off offset:2048
	global_store_short v[250:251], v30, off
	global_store_short v[250:251], v31, off offset:2048
	global_load_dwordx4 v[144:147], v[222:223], off offset:384
	global_load_dwordx4 v[148:151], v[222:223], off offset:416
	global_load_dwordx4 v[152:155], v[222:223], off offset:448
	global_load_dwordx4 v[156:159], v[222:223], off offset:480
	s_mov_b32 s100, 0x18000
	v_lshl_add_u64 v[228:229], v[214:215], 0, s[100:101]
	global_load_ushort v176, v[228:229], off
	global_load_ushort v177, v[228:229], off offset:1024
	global_load_ushort v178, v[228:229], off offset:2048
	global_load_ushort v179, v[228:229], off offset:3072
	s_mov_b32 s100, 0x1a000
	v_lshl_add_u64 v[230:231], v[214:215], 0, s[100:101]
	global_load_ushort v180, v[230:231], off
	global_load_ushort v181, v[230:231], off offset:1024
	global_load_ushort v182, v[230:231], off offset:2048
	global_load_ushort v183, v[230:231], off offset:3072
	s_mov_b32 s100, 0x1c000
	v_lshl_add_u64 v[232:233], v[214:215], 0, s[100:101]
	global_load_ushort v184, v[232:233], off
	global_load_ushort v185, v[232:233], off offset:1024
	global_load_ushort v186, v[232:233], off offset:2048
	global_load_ushort v187, v[232:233], off offset:3072
	s_mov_b32 s100, 0x1e000
	v_lshl_add_u64 v[234:235], v[214:215], 0, s[100:101]
	global_load_ushort v188, v[234:235], off
	global_load_ushort v189, v[234:235], off offset:1024
	global_load_ushort v190, v[234:235], off offset:2048
	global_load_ushort v191, v[234:235], off offset:3072
	s_mov_b32 s100, 0x30000
	v_lshl_add_u64 v[236:237], v[218:219], 0, s[100:101]
	s_mov_b32 s100, 0x31000
	v_lshl_add_u64 v[238:239], v[218:219], 0, s[100:101]
	s_mov_b32 s100, 0x34000
	v_lshl_add_u64 v[240:241], v[218:219], 0, s[100:101]
	s_mov_b32 s100, 0x35000
	v_lshl_add_u64 v[242:243], v[218:219], 0, s[100:101]
	s_mov_b32 s100, 0x38000
	v_lshl_add_u64 v[244:245], v[218:219], 0, s[100:101]
	s_mov_b32 s100, 0x39000
	v_lshl_add_u64 v[246:247], v[218:219], 0, s[100:101]
	s_mov_b32 s100, 0x3c000
	v_lshl_add_u64 v[248:249], v[218:219], 0, s[100:101]
	s_mov_b32 s100, 0x3d000
	v_lshl_add_u64 v[250:251], v[218:219], 0, s[100:101]
	s_waitcnt vmcnt(0)
; __device__ __forceinline__ bf16_t f2bf(float f) { return (bf16_t)(pk2(f, 0.f) & 0xffffu); }
;   __device__ __forceinline__ void operator()(f32x16 (&acc)[2][2], int fbase, int tbase, int lane, const float (&pre)[2]) const {
;     ...
;     for (int qi = 0; qi < 2; ++qi) {
;       const unsigned tok0 = (unsigned)(chunk * 128 + fbase + 4 * h);
;       const unsigned uo = tok0 * 512u + (unsigned)(g * 64 + 32 * qi + r), mo = tok0 * 1024u + (unsigned)(g * 64 + 32 * qi + r);
; #pragma unroll
;       for (int pi = 0; pi < 2; ++pi)
; #pragma unroll
;         for (int i = 0; i < 16; ++i) {
;           const int io = 32 * pi + 8 * (i >> 2) + (i & 3);
;           const float uu = bf2f(ub[uo + (unsigned)(io * 512)]);
;           mix[mo + (unsigned)(io * 1024)] = f2bf(uu * (acc[pi][qi][i] + bs[io]));
;         }
;     }
	v_lshlrev_b32_e32 v176, 16, v176
	v_add_f32_e32 v32, v32, v144
	v_lshlrev_b32_e32 v177, 16, v177
	v_add_f32_e32 v33, v33, v145
	v_lshlrev_b32_e32 v178, 16, v178
	v_add_f32_e32 v34, v34, v146
	v_lshlrev_b32_e32 v179, 16, v179
	v_add_f32_e32 v35, v35, v147
	v_lshlrev_b32_e32 v180, 16, v180
	v_add_f32_e32 v36, v36, v148
	v_lshlrev_b32_e32 v181, 16, v181
	v_add_f32_e32 v37, v37, v149
	v_lshlrev_b32_e32 v182, 16, v182
	v_add_f32_e32 v38, v38, v150
	v_lshlrev_b32_e32 v183, 16, v183
	v_add_f32_e32 v39, v39, v151
	v_lshlrev_b32_e32 v184, 16, v184
	v_add_f32_e32 v40, v40, v152
	v_lshlrev_b32_e32 v185, 16, v185
	v_add_f32_e32 v41, v41, v153
	v_lshlrev_b32_e32 v186, 16, v186
	v_add_f32_e32 v42, v42, v154
	v_lshlrev_b32_e32 v187, 16, v187
	v_add_f32_e32 v43, v43, v155
	v_lshlrev_b32_e32 v188, 16, v188
	v_add_f32_e32 v44, v44, v156
	v_lshlrev_b32_e32 v189, 16, v189
	v_add_f32_e32 v45, v45, v157
	v_lshlrev_b32_e32 v190, 16, v190
	v_add_f32_e32 v46, v46, v158
	v_lshlrev_b32_e32 v191, 16, v191
	v_add_f32_e32 v47, v47, v159
	v_mul_f32_e32 v32, v32, v176
	v_mul_f32_e32 v33, v33, v177
	v_mul_f32_e32 v34, v34, v178
	v_mul_f32_e32 v35, v35, v179
	v_mul_f32_e32 v36, v36, v180
	v_mul_f32_e32 v37, v37, v181
	v_mul_f32_e32 v38, v38, v182
	v_mul_f32_e32 v39, v39, v183
	v_mul_f32_e32 v40, v40, v184
	v_mul_f32_e32 v41, v41, v185
	v_mul_f32_e32 v42, v42, v186
	v_mul_f32_e32 v43, v43, v187
	v_mul_f32_e32 v44, v44, v188
	v_mul_f32_e32 v45, v45, v189
	v_mul_f32_e32 v46, v46, v190
	v_mul_f32_e32 v47, v47, v191
	v_cvt_pk_bf16_f32 v32, v32, v32
	v_cvt_pk_bf16_f32 v33, v33, v33
	v_cvt_pk_bf16_f32 v34, v34, v34
	v_cvt_pk_bf16_f32 v35, v35, v35
	v_cvt_pk_bf16_f32 v36, v36, v36
	v_cvt_pk_bf16_f32 v37, v37, v37
	v_cvt_pk_bf16_f32 v38, v38, v38
	v_cvt_pk_bf16_f32 v39, v39, v39
	v_cvt_pk_bf16_f32 v40, v40, v40
	v_cvt_pk_bf16_f32 v41, v41, v41
	v_cvt_pk_bf16_f32 v42, v42, v42
	v_cvt_pk_bf16_f32 v43, v43, v43
	v_cvt_pk_bf16_f32 v44, v44, v44
	v_cvt_pk_bf16_f32 v45, v45, v45
	v_cvt_pk_bf16_f32 v46, v46, v46
	v_cvt_pk_bf16_f32 v47, v47, v47
	global_store_short v[236:237], v32, off
	global_store_short v[236:237], v33, off offset:2048
	global_store_short v[238:239], v34, off
	global_store_short v[238:239], v35, off offset:2048
	global_store_short v[240:241], v36, off
	global_store_short v[240:241], v37, off offset:2048
	global_store_short v[242:243], v38, off
	global_store_short v[242:243], v39, off offset:2048
	global_store_short v[244:245], v40, off
	global_store_short v[244:245], v41, off offset:2048
	global_store_short v[246:247], v42, off
	global_store_short v[246:247], v43, off offset:2048
	global_store_short v[248:249], v44, off
	global_store_short v[248:249], v45, off offset:2048
	global_store_short v[250:251], v46, off
	global_store_short v[250:251], v47, off offset:2048
	s_mov_b32 s100, 0x18000
	v_lshl_add_u64 v[228:229], v[216:217], 0, s[100:101]
	global_load_ushort v176, v[228:229], off
	global_load_ushort v177, v[228:229], off offset:1024
	global_load_ushort v178, v[228:229], off offset:2048
	global_load_ushort v179, v[228:229], off offset:3072
	s_mov_b32 s100, 0x1a000
	v_lshl_add_u64 v[230:231], v[216:217], 0, s[100:101]
	global_load_ushort v180, v[230:231], off
	global_load_ushort v181, v[230:231], off offset:1024
	global_load_ushort v182, v[230:231], off offset:2048
	global_load_ushort v183, v[230:231], off offset:3072
	s_mov_b32 s100, 0x1c000
	v_lshl_add_u64 v[232:233], v[216:217], 0, s[100:101]
	global_load_ushort v184, v[232:233], off
	global_load_ushort v185, v[232:233], off offset:1024
	global_load_ushort v186, v[232:233], off offset:2048
	global_load_ushort v187, v[232:233], off offset:3072
	s_mov_b32 s100, 0x1e000
	v_lshl_add_u64 v[234:235], v[216:217], 0, s[100:101]
	global_load_ushort v188, v[234:235], off
	global_load_ushort v189, v[234:235], off offset:1024
	global_load_ushort v190, v[234:235], off offset:2048
	global_load_ushort v191, v[234:235], off offset:3072
	s_mov_b32 s100, 0x30000
	v_lshl_add_u64 v[236:237], v[220:221], 0, s[100:101]
	s_mov_b32 s100, 0x31000
	v_lshl_add_u64 v[238:239], v[220:221], 0, s[100:101]
	s_mov_b32 s100, 0x34000
	v_lshl_add_u64 v[240:241], v[220:221], 0, s[100:101]
	s_mov_b32 s100, 0x35000
	v_lshl_add_u64 v[242:243], v[220:221], 0, s[100:101]
	s_mov_b32 s100, 0x38000
	v_lshl_add_u64 v[244:245], v[220:221], 0, s[100:101]
	s_mov_b32 s100, 0x39000
	v_lshl_add_u64 v[246:247], v[220:221], 0, s[100:101]
	s_mov_b32 s100, 0x3c000
	v_lshl_add_u64 v[248:249], v[220:221], 0, s[100:101]
	s_mov_b32 s100, 0x3d000
	v_lshl_add_u64 v[250:251], v[220:221], 0, s[100:101]
	s_waitcnt vmcnt(0)
; __device__ __forceinline__ bf16_t f2bf(float f) { return (bf16_t)(pk2(f, 0.f) & 0xffffu); }
; template <bool FULL, int MODE, class Epi>
; __device__ __forceinline__ void gemm_phase(const bf16_t* __restrict__ P, int ldp, int NP, const bf16_t* __restrict__ Q, int ldq, int K, char* smem, const Epi& epi, int wv) {
;     ...
;       epi(*(f32x16 (*)[2][2])(&acc[0]), p0 + wp * 128, q0 + wq * 64, lane, pre);
;       epi(*(f32x16 (*)[2][2])(&acc[2]), p0 + wp * 128 + 64, q0 + wq * 64, lane, pre);
;     }
;     if (!has_next) break;
;     ++it; p0 = np0; q0 = nq0;
;     if (!Epi::XPF) {
;       gp = P + (size_t)(p0 + lr) * ldp + lc * 8; gq = Q + (size_t)(q0 + lr) * ldq + lc * 8;
; #pragma unroll
;       for (int j = 0; j < 4; ++j) { rp[j] = *(const u32x4*)(gp + (size_t)(64 * j) * ldp + rot * 64); rq[j] = *(const u32x4*)(gq + (size_t)(64 * j) * ldq + rot * 64); }
;   __device__ __forceinline__ void operator()(f32x16 (&acc)[2][2], int fbase, int tbase, int lane, const float (&pre)[2]) const {
;     ...
;     for (int qi = 0; qi < 2; ++qi) {
;       const unsigned tok0 = (unsigned)(chunk * 128 + fbase + 4 * h);
;       const unsigned uo = tok0 * 512u + (unsigned)(g * 64 + 32 * qi + r), mo = tok0 * 1024u + (unsigned)(g * 64 + 32 * qi + r);
; #pragma unroll
;       for (int pi = 0; pi < 2; ++pi)
; #pragma unroll
;         for (int i = 0; i < 16; ++i) {
;           const int io = 32 * pi + 8 * (i >> 2) + (i & 3);
;           const float uu = bf2f(ub[uo + (unsigned)(io * 512)]);
;           mix[mo + (unsigned)(io * 1024)] = f2bf(uu * (acc[pi][qi][i] + bs[io]));
;         }
;     }
	v_lshlrev_b32_e32 v176, 16, v176
	v_add_f32_e32 v0, v0, v144
	v_lshlrev_b32_e32 v177, 16, v177
	v_add_f32_e32 v1, v1, v145
	v_lshlrev_b32_e32 v178, 16, v178
	v_add_f32_e32 v2, v2, v146
	v_lshlrev_b32_e32 v179, 16, v179
	v_add_f32_e32 v3, v3, v147
	v_lshlrev_b32_e32 v180, 16, v180
	v_add_f32_e32 v4, v4, v148
	v_lshlrev_b32_e32 v181, 16, v181
	v_add_f32_e32 v5, v5, v149
	v_lshlrev_b32_e32 v182, 16, v182
	v_add_f32_e32 v6, v6, v150
	v_lshlrev_b32_e32 v183, 16, v183
	v_add_f32_e32 v7, v7, v151
	v_lshlrev_b32_e32 v184, 16, v184
	v_add_f32_e32 v8, v8, v152
	v_lshlrev_b32_e32 v185, 16, v185
	v_add_f32_e32 v9, v9, v153
	v_lshlrev_b32_e32 v186, 16, v186
	v_add_f32_e32 v10, v10, v154
	v_lshlrev_b32_e32 v187, 16, v187
	v_add_f32_e32 v11, v11, v155
	v_lshlrev_b32_e32 v188, 16, v188
	v_add_f32_e32 v12, v12, v156
	v_lshlrev_b32_e32 v189, 16, v189
	v_add_f32_e32 v13, v13, v157
	v_lshlrev_b32_e32 v190, 16, v190
	v_add_f32_e32 v14, v14, v158
	v_lshlrev_b32_e32 v191, 16, v191
	v_add_f32_e32 v15, v15, v159
	v_mul_f32_e32 v0, v0, v176
	v_mul_f32_e32 v1, v1, v177
	v_mul_f32_e32 v2, v2, v178
	v_mul_f32_e32 v3, v3, v179
	v_mul_f32_e32 v4, v4, v180
	v_mul_f32_e32 v5, v5, v181
	v_mul_f32_e32 v6, v6, v182
	v_mul_f32_e32 v7, v7, v183
	v_mul_f32_e32 v8, v8, v184
	v_mul_f32_e32 v9, v9, v185
	v_mul_f32_e32 v10, v10, v186
	v_mul_f32_e32 v11, v11, v187
	v_mul_f32_e32 v12, v12, v188
	v_mul_f32_e32 v13, v13, v189
	v_mul_f32_e32 v14, v14, v190
	v_mul_f32_e32 v15, v15, v191
	v_cvt_pk_bf16_f32 v0, v0, v0
	v_cvt_pk_bf16_f32 v1, v1, v1
	v_cvt_pk_bf16_f32 v2, v2, v2
	v_cvt_pk_bf16_f32 v3, v3, v3
	v_cvt_pk_bf16_f32 v4, v4, v4
	v_cvt_pk_bf16_f32 v5, v5, v5
	v_cvt_pk_bf16_f32 v6, v6, v6
	v_cvt_pk_bf16_f32 v7, v7, v7
	v_cvt_pk_bf16_f32 v8, v8, v8
	v_cvt_pk_bf16_f32 v9, v9, v9
	v_cvt_pk_bf16_f32 v10, v10, v10
	v_cvt_pk_bf16_f32 v11, v11, v11
	v_cvt_pk_bf16_f32 v12, v12, v12
	v_cvt_pk_bf16_f32 v13, v13, v13
	v_cvt_pk_bf16_f32 v14, v14, v14
	v_cvt_pk_bf16_f32 v15, v15, v15
	global_store_short v[236:237], v0, off
	global_store_short v[236:237], v1, off offset:2048
	global_store_short v[238:239], v2, off
	global_store_short v[238:239], v3, off offset:2048
	global_store_short v[240:241], v4, off
	global_store_short v[240:241], v5, off offset:2048
	global_store_short v[242:243], v6, off
	global_store_short v[242:243], v7, off offset:2048
	global_store_short v[244:245], v8, off
	global_store_short v[244:245], v9, off offset:2048
	global_store_short v[246:247], v10, off
	global_store_short v[246:247], v11, off offset:2048
	global_store_short v[248:249], v12, off
	global_store_short v[248:249], v13, off offset:2048
	global_store_short v[250:251], v14, off
	global_store_short v[250:251], v15, off offset:2048
.LBB0_566:
	s_or_b64 exec, exec, s[12:13]
	v_add_u32_e32 v64, 64, v142
	v_cmp_gt_i32_e32 vcc, s3, v64
	s_and_saveexec_b64 s[12:13], vcc
	s_cbranch_execz .LBB0_568
.LBB0_568:
	s_or_b64 exec, exec, s[12:13]
	s_andn2_b64 vcc, exec, s[10:11]
	s_mov_b64 s[10:11], -1
	s_cbranch_vccnz .LBB0_556
	v_add_u32_e32 v0, s18, v173
	v_add_u32_e32 v2, s67, v173
	v_ashrrev_i32_e32 v1, 31, v0
	v_ashrrev_i32_e32 v3, 31, v2
	v_lshlrev_b64 v[0:1], 8, v[0:1]
	v_lshlrev_b64 v[2:3], 8, v[2:3]
	v_lshl_add_u64 v[0:1], v[166:167], 0, v[0:1]
	v_lshl_add_u64 v[2:3], v[168:169], 0, v[2:3]
	s_mov_b64 s[10:11], 0
	s_branch .LBB0_556
